# back-edge rotation: K-loop counter/pointer bumps and exit test moved in front of the loop-back barrier in the four GEMM K-loops
# baseline (speedup 1.0000x reference)
.LBB0_589:
	s_add_u32 s40, s38, 0xfff80080
	s_addc_u32 s41, s39, -1
	s_cmp_eq_u32 s60, 28
	s_cselect_b32 s43, s11, s41
	s_cselect_b32 s42, s56, s40
	s_cselect_b32 s41, s15, s59
	s_cselect_b32 s40, s57, s58
	s_add_i32 s61, 0, 0x10000
	v_add_u32_e32 v34, s61, v213
	s_add_i32 s64, 0, 0x14000
	ds_read_b128 v[132:135], v34
	ds_read_b128 v[136:139], v34 offset:1024
	ds_read_b128 v[140:143], v34 offset:2048
	ds_read_b128 v[144:147], v34 offset:3072
	v_add_u32_e32 v34, s64, v213
	ds_read_b128 v[148:151], v34
	ds_read_b128 v[152:155], v34 offset:1024
	ds_read_b128 v[156:159], v34 offset:2048
	ds_read_b128 v[160:163], v34 offset:3072
	v_lshl_add_u64 v[184:185], s[38:39], 0, v[198:199]
	s_add_i32 m0, s47, 0xc000
	ds_read_b128 v[164:167], v219
	ds_read_b128 v[168:171], v219 offset:1024
	ds_read_b128 v[172:175], v219 offset:2048
	ds_read_b128 v[176:179], v219 offset:3072
	ds_read_b128 v[202:205], v219 offset:4096
	ds_read_b128 v[206:209], v219 offset:5120
	ds_read_b128 v[220:223], v219 offset:6144
	ds_read_b128 v[224:227], v219 offset:7168
	global_load_lds_dwordx4 v[184:185], off
	v_lshl_add_u64 v[184:185], s[38:39], 0, v[200:201]
	s_add_i32 m0, s47, 0xe000
	s_nop 0
	global_load_lds_dwordx4 v[184:185], off
	s_waitcnt vmcnt(8)
	s_waitcnt lgkmcnt(0)
	s_barrier
	s_setprio 1
	s_waitcnt lgkmcnt(0)
	v_mfma_f32_16x16x32_bf16 v[128:131], v[132:135], v[164:167], v[128:131]
	v_mfma_f32_16x16x32_bf16 v[124:127], v[140:143], v[164:167], v[124:127]
	v_mfma_f32_16x16x32_bf16 v[112:115], v[132:135], v[172:175], v[112:115]
	v_mfma_f32_16x16x32_bf16 v[108:111], v[140:143], v[172:175], v[108:111]
	v_mfma_f32_16x16x32_bf16 v[96:99], v[132:135], v[202:205], v[96:99]
	v_mfma_f32_16x16x32_bf16 v[92:95], v[140:143], v[202:205], v[92:95]
	v_mfma_f32_16x16x32_bf16 v[80:83], v[132:135], v[220:223], v[80:83]
	v_mfma_f32_16x16x32_bf16 v[76:79], v[140:143], v[220:223], v[76:79]
	v_mfma_f32_16x16x32_bf16 v[128:131], v[136:139], v[168:171], v[128:131]
	v_mfma_f32_16x16x32_bf16 v[124:127], v[144:147], v[168:171], v[124:127]
	v_mfma_f32_16x16x32_bf16 v[112:115], v[136:139], v[176:179], v[112:115]
	v_mfma_f32_16x16x32_bf16 v[108:111], v[144:147], v[176:179], v[108:111]
	v_mfma_f32_16x16x32_bf16 v[96:99], v[136:139], v[206:209], v[96:99]
	v_mfma_f32_16x16x32_bf16 v[92:95], v[144:147], v[206:209], v[92:95]
	v_mfma_f32_16x16x32_bf16 v[80:83], v[136:139], v[224:227], v[80:83]
	v_mfma_f32_16x16x32_bf16 v[76:79], v[144:147], v[224:227], v[76:79]
	s_setprio 0
	s_setprio 1
	v_mfma_f32_16x16x32_bf16 v[120:123], v[148:151], v[164:167], v[120:123]
	v_mfma_f32_16x16x32_bf16 v[116:119], v[156:159], v[164:167], v[116:119]
	v_mfma_f32_16x16x32_bf16 v[104:107], v[148:151], v[172:175], v[104:107]
	v_mfma_f32_16x16x32_bf16 v[100:103], v[156:159], v[172:175], v[100:103]
	v_mfma_f32_16x16x32_bf16 v[88:91], v[148:151], v[202:205], v[88:91]
	v_mfma_f32_16x16x32_bf16 v[84:87], v[156:159], v[202:205], v[84:87]
	v_mfma_f32_16x16x32_bf16 v[72:75], v[148:151], v[220:223], v[72:75]
	v_mfma_f32_16x16x32_bf16 v[68:71], v[156:159], v[220:223], v[68:71]
	v_mfma_f32_16x16x32_bf16 v[120:123], v[152:155], v[168:171], v[120:123]
	v_mfma_f32_16x16x32_bf16 v[116:119], v[160:163], v[168:171], v[116:119]
	v_mfma_f32_16x16x32_bf16 v[104:107], v[152:155], v[176:179], v[104:107]
	v_mfma_f32_16x16x32_bf16 v[100:103], v[160:163], v[176:179], v[100:103]
	v_mfma_f32_16x16x32_bf16 v[88:91], v[152:155], v[206:209], v[88:91]
	v_mfma_f32_16x16x32_bf16 v[84:87], v[160:163], v[206:209], v[84:87]
	v_mfma_f32_16x16x32_bf16 v[72:75], v[152:155], v[224:227], v[72:75]
	v_mfma_f32_16x16x32_bf16 v[68:71], v[160:163], v[224:227], v[68:71]
	s_setprio 0
	s_barrier
	s_add_i32 s61, s61, s46
	v_lshl_add_u64 v[184:185], s[40:41], 0, v[190:191]
	s_mov_b32 m0, s61
	ds_read_b128 v[164:167], v219 offset:16384
	ds_read_b128 v[168:171], v219 offset:17408
	ds_read_b128 v[172:175], v219 offset:18432
	ds_read_b128 v[176:179], v219 offset:19456
	ds_read_b128 v[202:205], v219 offset:20480
	ds_read_b128 v[206:209], v219 offset:21504
	ds_read_b128 v[220:223], v219 offset:22528
	ds_read_b128 v[224:227], v219 offset:23552
	global_load_lds_dwordx4 v[184:185], off
	s_add_i32 m0, s61, 0x2000
	s_add_u32 s62, s40, 0x80000
	v_lshl_add_u64 v[186:187], s[40:41], 0, v[180:181]
	s_addc_u32 s63, s41, 0
	s_add_i32 s61, s64, s46
	global_load_lds_dwordx4 v[186:187], off
	v_lshl_add_u64 v[188:189], s[62:63], 0, v[190:191]
	s_mov_b32 m0, s61
	v_lshl_add_u64 v[210:211], s[42:43], 0, v[182:183]
	global_load_lds_dwordx4 v[188:189], off
	v_lshl_add_u64 v[188:189], s[62:63], 0, v[180:181]
	s_add_i32 m0, s61, 0x2000
	s_nop 0
	global_load_lds_dwordx4 v[188:189], off
	v_lshl_add_u64 v[188:189], s[42:43], 0, v[192:193]
	s_mov_b32 m0, s47
	s_nop 0
	global_load_lds_dwordx4 v[188:189], off
	s_mov_b32 m0, s48
	s_nop 0
	global_load_lds_dwordx4 v[210:211], off
	s_waitcnt vmcnt(8)
	s_waitcnt lgkmcnt(0)
	s_barrier
	s_setprio 1
	s_waitcnt lgkmcnt(0)
	v_mfma_f32_16x16x32_bf16 v[64:67], v[132:135], v[164:167], v[64:67]
	v_mfma_f32_16x16x32_bf16 v[60:63], v[140:143], v[164:167], v[60:63]
	v_mfma_f32_16x16x32_bf16 v[48:51], v[132:135], v[172:175], v[48:51]
	v_mfma_f32_16x16x32_bf16 v[44:47], v[140:143], v[172:175], v[44:47]
	v_mfma_f32_16x16x32_bf16 v[30:33], v[132:135], v[202:205], v[30:33]
	v_mfma_f32_16x16x32_bf16 v[26:29], v[140:143], v[202:205], v[26:29]
	v_mfma_f32_16x16x32_bf16 v[14:17], v[132:135], v[220:223], v[14:17]
	v_mfma_f32_16x16x32_bf16 v[10:13], v[140:143], v[220:223], v[10:13]
	v_mfma_f32_16x16x32_bf16 v[64:67], v[136:139], v[168:171], v[64:67]
	v_mfma_f32_16x16x32_bf16 v[60:63], v[144:147], v[168:171], v[60:63]
	v_mfma_f32_16x16x32_bf16 v[48:51], v[136:139], v[176:179], v[48:51]
	v_mfma_f32_16x16x32_bf16 v[44:47], v[144:147], v[176:179], v[44:47]
	v_mfma_f32_16x16x32_bf16 v[30:33], v[136:139], v[206:209], v[30:33]
	v_mfma_f32_16x16x32_bf16 v[26:29], v[144:147], v[206:209], v[26:29]
	v_mfma_f32_16x16x32_bf16 v[14:17], v[136:139], v[224:227], v[14:17]
	v_mfma_f32_16x16x32_bf16 v[10:13], v[144:147], v[224:227], v[10:13]
	s_setprio 0
	s_setprio 1
	v_mfma_f32_16x16x32_bf16 v[56:59], v[148:151], v[164:167], v[56:59]
	v_mfma_f32_16x16x32_bf16 v[52:55], v[156:159], v[164:167], v[52:55]
	v_mfma_f32_16x16x32_bf16 v[40:43], v[148:151], v[172:175], v[40:43]
	v_mfma_f32_16x16x32_bf16 v[36:39], v[156:159], v[172:175], v[36:39]
	v_mfma_f32_16x16x32_bf16 v[22:25], v[148:151], v[202:205], v[22:25]
	v_mfma_f32_16x16x32_bf16 v[18:21], v[156:159], v[202:205], v[18:21]
	v_mfma_f32_16x16x32_bf16 v[6:9], v[148:151], v[220:223], v[6:9]
	v_mfma_f32_16x16x32_bf16 v[2:5], v[156:159], v[220:223], v[2:5]
	v_mfma_f32_16x16x32_bf16 v[56:59], v[152:155], v[168:171], v[56:59]
	v_mfma_f32_16x16x32_bf16 v[52:55], v[160:163], v[168:171], v[52:55]
	v_mfma_f32_16x16x32_bf16 v[40:43], v[152:155], v[176:179], v[40:43]
	v_mfma_f32_16x16x32_bf16 v[36:39], v[160:163], v[176:179], v[36:39]
	v_mfma_f32_16x16x32_bf16 v[22:25], v[152:155], v[206:209], v[22:25]
	v_mfma_f32_16x16x32_bf16 v[18:21], v[160:163], v[206:209], v[18:21]
	v_mfma_f32_16x16x32_bf16 v[6:9], v[152:155], v[224:227], v[6:9]
	v_mfma_f32_16x16x32_bf16 v[2:5], v[160:163], v[224:227], v[2:5]
	s_setprio 0
	s_barrier
	s_add_i32 s61, 0, 0x18000
	v_add_u32_e32 v34, s61, v213
	s_add_i32 s62, 0, 0x1c000
	ds_read_b128 v[132:135], v34
	ds_read_b128 v[136:139], v34 offset:1024
	ds_read_b128 v[140:143], v34 offset:2048
	ds_read_b128 v[144:147], v34 offset:3072
	v_add_u32_e32 v34, s62, v213
	ds_read_b128 v[148:151], v34
	ds_read_b128 v[152:155], v34 offset:1024
	ds_read_b128 v[156:159], v34 offset:2048
	ds_read_b128 v[160:163], v34 offset:3072
	s_add_u32 s42, s42, 0x80000
	s_addc_u32 s43, s43, 0
	s_mov_b32 m0, s49
	v_lshl_add_u64 v[228:229], s[42:43], 0, v[192:193]
	ds_read_b128 v[164:167], v219 offset:32768
	ds_read_b128 v[168:171], v219 offset:33792
	ds_read_b128 v[172:175], v219 offset:34816
	ds_read_b128 v[176:179], v219 offset:35840
	ds_read_b128 v[202:205], v219 offset:36864
	ds_read_b128 v[206:209], v219 offset:37888
	ds_read_b128 v[220:223], v219 offset:38912
	ds_read_b128 v[224:227], v219 offset:39936
	global_load_lds_dwordx4 v[228:229], off
	v_lshl_add_u64 v[228:229], s[42:43], 0, v[182:183]
	s_mov_b32 m0, s50
	s_nop 0
	global_load_lds_dwordx4 v[228:229], off
	s_waitcnt vmcnt(8)
	s_waitcnt lgkmcnt(0)
	s_barrier
	s_setprio 1
	s_waitcnt lgkmcnt(0)
	v_mfma_f32_16x16x32_bf16 v[128:131], v[132:135], v[164:167], v[128:131]
	v_mfma_f32_16x16x32_bf16 v[124:127], v[140:143], v[164:167], v[124:127]
	v_mfma_f32_16x16x32_bf16 v[112:115], v[132:135], v[172:175], v[112:115]
	v_mfma_f32_16x16x32_bf16 v[108:111], v[140:143], v[172:175], v[108:111]
	v_mfma_f32_16x16x32_bf16 v[96:99], v[132:135], v[202:205], v[96:99]
	v_mfma_f32_16x16x32_bf16 v[92:95], v[140:143], v[202:205], v[92:95]
	v_mfma_f32_16x16x32_bf16 v[80:83], v[132:135], v[220:223], v[80:83]
	v_mfma_f32_16x16x32_bf16 v[76:79], v[140:143], v[220:223], v[76:79]
	v_mfma_f32_16x16x32_bf16 v[128:131], v[136:139], v[168:171], v[128:131]
	v_mfma_f32_16x16x32_bf16 v[124:127], v[144:147], v[168:171], v[124:127]
	v_mfma_f32_16x16x32_bf16 v[112:115], v[136:139], v[176:179], v[112:115]
	v_mfma_f32_16x16x32_bf16 v[108:111], v[144:147], v[176:179], v[108:111]
	v_mfma_f32_16x16x32_bf16 v[96:99], v[136:139], v[206:209], v[96:99]
	v_mfma_f32_16x16x32_bf16 v[92:95], v[144:147], v[206:209], v[92:95]
	v_mfma_f32_16x16x32_bf16 v[80:83], v[136:139], v[224:227], v[80:83]
	v_mfma_f32_16x16x32_bf16 v[76:79], v[144:147], v[224:227], v[76:79]
	s_setprio 0
	s_setprio 1
	v_mfma_f32_16x16x32_bf16 v[120:123], v[148:151], v[164:167], v[120:123]
	v_mfma_f32_16x16x32_bf16 v[116:119], v[156:159], v[164:167], v[116:119]
	v_mfma_f32_16x16x32_bf16 v[104:107], v[148:151], v[172:175], v[104:107]
	v_mfma_f32_16x16x32_bf16 v[100:103], v[156:159], v[172:175], v[100:103]
	v_mfma_f32_16x16x32_bf16 v[88:91], v[148:151], v[202:205], v[88:91]
	v_mfma_f32_16x16x32_bf16 v[84:87], v[156:159], v[202:205], v[84:87]
	v_mfma_f32_16x16x32_bf16 v[72:75], v[148:151], v[220:223], v[72:75]
	v_mfma_f32_16x16x32_bf16 v[68:71], v[156:159], v[220:223], v[68:71]
	v_mfma_f32_16x16x32_bf16 v[120:123], v[152:155], v[168:171], v[120:123]
	v_mfma_f32_16x16x32_bf16 v[116:119], v[160:163], v[168:171], v[116:119]
	v_mfma_f32_16x16x32_bf16 v[104:107], v[152:155], v[176:179], v[104:107]
	v_mfma_f32_16x16x32_bf16 v[100:103], v[160:163], v[176:179], v[100:103]
	v_mfma_f32_16x16x32_bf16 v[88:91], v[152:155], v[206:209], v[88:91]
	v_mfma_f32_16x16x32_bf16 v[84:87], v[160:163], v[206:209], v[84:87]
	v_mfma_f32_16x16x32_bf16 v[72:75], v[152:155], v[224:227], v[72:75]
	v_mfma_f32_16x16x32_bf16 v[68:71], v[160:163], v[224:227], v[68:71]
	s_setprio 0
	s_barrier
	s_add_i32 s42, s61, s46
	v_lshl_add_u64 v[184:185], v[184:185], 0, s[96:97]
	s_mov_b32 m0, s42
	ds_read_b128 v[164:167], v219 offset:49152
	ds_read_b128 v[168:171], v219 offset:50176
	ds_read_b128 v[172:175], v219 offset:51200
	ds_read_b128 v[176:179], v219 offset:52224
	ds_read_b128 v[202:205], v219 offset:53248
	ds_read_b128 v[206:209], v219 offset:54272
	ds_read_b128 v[220:223], v219 offset:55296
	ds_read_b128 v[224:227], v219 offset:56320
	global_load_lds_dwordx4 v[184:185], off
	s_add_i32 m0, s42, 0x2000
	s_add_u32 s40, s40, 0x80080
	v_lshl_add_u64 v[184:185], v[186:187], 0, s[96:97]
	s_addc_u32 s41, s41, 0
	s_add_i32 s42, s62, s46
	global_load_lds_dwordx4 v[184:185], off
	v_lshl_add_u64 v[184:185], s[40:41], 0, v[190:191]
	s_mov_b32 m0, s42
	s_nop 0
	global_load_lds_dwordx4 v[184:185], off
	v_lshl_add_u64 v[184:185], s[40:41], 0, v[180:181]
	s_add_i32 m0, s42, 0x2000
	s_nop 0
	global_load_lds_dwordx4 v[184:185], off
	v_lshl_add_u64 v[184:185], v[188:189], 0, s[96:97]
	s_mov_b32 m0, s51
	s_nop 0
	global_load_lds_dwordx4 v[184:185], off
	v_lshl_add_u64 v[184:185], v[210:211], 0, s[96:97]
	s_mov_b32 m0, s52
	s_nop 0
	global_load_lds_dwordx4 v[184:185], off
	s_waitcnt vmcnt(8)
	s_waitcnt lgkmcnt(0)
	s_barrier
	s_setprio 1
	s_waitcnt lgkmcnt(0)
	v_mfma_f32_16x16x32_bf16 v[64:67], v[132:135], v[164:167], v[64:67]
	v_mfma_f32_16x16x32_bf16 v[60:63], v[140:143], v[164:167], v[60:63]
	v_mfma_f32_16x16x32_bf16 v[48:51], v[132:135], v[172:175], v[48:51]
	v_mfma_f32_16x16x32_bf16 v[44:47], v[140:143], v[172:175], v[44:47]
	v_mfma_f32_16x16x32_bf16 v[30:33], v[132:135], v[202:205], v[30:33]
	v_mfma_f32_16x16x32_bf16 v[26:29], v[140:143], v[202:205], v[26:29]
	v_mfma_f32_16x16x32_bf16 v[14:17], v[132:135], v[220:223], v[14:17]
	v_mfma_f32_16x16x32_bf16 v[10:13], v[140:143], v[220:223], v[10:13]
	v_mfma_f32_16x16x32_bf16 v[64:67], v[136:139], v[168:171], v[64:67]
	v_mfma_f32_16x16x32_bf16 v[60:63], v[144:147], v[168:171], v[60:63]
	v_mfma_f32_16x16x32_bf16 v[48:51], v[136:139], v[176:179], v[48:51]
	v_mfma_f32_16x16x32_bf16 v[44:47], v[144:147], v[176:179], v[44:47]
	v_mfma_f32_16x16x32_bf16 v[30:33], v[136:139], v[206:209], v[30:33]
	v_mfma_f32_16x16x32_bf16 v[26:29], v[144:147], v[206:209], v[26:29]
	v_mfma_f32_16x16x32_bf16 v[14:17], v[136:139], v[224:227], v[14:17]
	v_mfma_f32_16x16x32_bf16 v[10:13], v[144:147], v[224:227], v[10:13]
	s_setprio 0
	s_setprio 1
	v_mfma_f32_16x16x32_bf16 v[56:59], v[148:151], v[164:167], v[56:59]
	v_mfma_f32_16x16x32_bf16 v[52:55], v[156:159], v[164:167], v[52:55]
	v_mfma_f32_16x16x32_bf16 v[40:43], v[148:151], v[172:175], v[40:43]
	v_mfma_f32_16x16x32_bf16 v[36:39], v[156:159], v[172:175], v[36:39]
	v_mfma_f32_16x16x32_bf16 v[22:25], v[148:151], v[202:205], v[22:25]
	v_mfma_f32_16x16x32_bf16 v[18:21], v[156:159], v[202:205], v[18:21]
	v_mfma_f32_16x16x32_bf16 v[6:9], v[148:151], v[220:223], v[6:9]
	v_mfma_f32_16x16x32_bf16 v[2:5], v[156:159], v[220:223], v[2:5]
	v_mfma_f32_16x16x32_bf16 v[56:59], v[152:155], v[168:171], v[56:59]
	v_mfma_f32_16x16x32_bf16 v[52:55], v[160:163], v[168:171], v[52:55]
	v_mfma_f32_16x16x32_bf16 v[40:43], v[152:155], v[176:179], v[40:43]
	v_mfma_f32_16x16x32_bf16 v[36:39], v[160:163], v[176:179], v[36:39]
	v_mfma_f32_16x16x32_bf16 v[22:25], v[152:155], v[206:209], v[22:25]
	v_mfma_f32_16x16x32_bf16 v[18:21], v[160:163], v[206:209], v[18:21]
	v_mfma_f32_16x16x32_bf16 v[6:9], v[152:155], v[224:227], v[6:9]
	v_mfma_f32_16x16x32_bf16 v[2:5], v[160:163], v[224:227], v[2:5]
	s_setprio 0
	s_add_i32 s60, s60, 2
	s_add_u32 s38, s38, 0x100
	s_addc_u32 s39, s39, 0
	s_add_u32 s58, s58, 0x100
	s_addc_u32 s59, s59, 0
	s_cmp_gt_u32 s60, 29
	s_barrier
	s_cbranch_scc0 .LBB0_589
	s_and_b64 vcc, exec, s[8:9]
	s_cbranch_vccz .LBB0_592
	s_barrier

.LBB0_1248:
	s_add_u32 s45, s8, s54
	s_addc_u32 s47, s9, s55
	s_add_u32 s56, s10, s54
	s_addc_u32 s57, s11, s55
	s_cmp_eq_u32 s61, s43
	s_cselect_b32 s59, s51, s47
	s_cselect_b32 s58, s50, s45
	s_cselect_b32 s57, s53, s57
	s_cselect_b32 s56, s52, s56
	s_add_i32 s45, 0, 0x10000
	s_add_i32 s47, 0, 0x14000
	v_add_u32_e32 v154, s45, v185
	v_add_u32_e32 v170, s47, v185
	ds_read_b128 v[136:139], v154
	ds_read_b128 v[140:143], v154 offset:1024
	ds_read_b128 v[144:147], v154 offset:2048
	ds_read_b128 v[154:157], v154 offset:3072
	ds_read_b128 v[158:161], v170
	ds_read_b128 v[162:165], v170 offset:1024
	ds_read_b128 v[166:169], v170 offset:2048
	ds_read_b128 v[170:173], v170 offset:3072
	v_lshl_add_u64 v[182:183], s[8:9], 0, v[134:135]
	s_add_i32 m0, s1, 0xc000
	ds_read_b128 v[174:177], v203
	ds_read_b128 v[178:181], v203 offset:1024
	ds_read_b128 v[186:189], v203 offset:2048
	ds_read_b128 v[190:193], v203 offset:3072
	ds_read_b128 v[194:197], v203 offset:4096
	ds_read_b128 v[198:201], v203 offset:5120
	ds_read_b128 v[204:207], v203 offset:6144
	ds_read_b128 v[208:211], v203 offset:7168
	global_load_lds_dwordx4 v[182:183], off
	v_lshl_add_u64 v[182:183], s[8:9], 0, v[132:133]
	s_add_i32 m0, s1, 0xe000
	s_nop 0
	global_load_lds_dwordx4 v[182:183], off
	s_waitcnt vmcnt(8)
	s_waitcnt lgkmcnt(0)
	s_barrier
	s_setprio 1
	s_waitcnt lgkmcnt(0)
	v_mfma_f32_16x16x32_bf16 v[128:131], v[136:139], v[174:177], v[128:131]
	v_mfma_f32_16x16x32_bf16 v[124:127], v[144:147], v[174:177], v[124:127]
	v_mfma_f32_16x16x32_bf16 v[120:123], v[136:139], v[186:189], v[120:123]
	v_mfma_f32_16x16x32_bf16 v[116:119], v[144:147], v[186:189], v[116:119]
	v_mfma_f32_16x16x32_bf16 v[112:115], v[136:139], v[194:197], v[112:115]
	v_mfma_f32_16x16x32_bf16 v[108:111], v[144:147], v[194:197], v[108:111]
	v_mfma_f32_16x16x32_bf16 v[104:107], v[136:139], v[204:207], v[104:107]
	v_mfma_f32_16x16x32_bf16 v[100:103], v[144:147], v[204:207], v[100:103]
	v_mfma_f32_16x16x32_bf16 v[128:131], v[140:143], v[178:181], v[128:131]
	v_mfma_f32_16x16x32_bf16 v[124:127], v[154:157], v[178:181], v[124:127]
	v_mfma_f32_16x16x32_bf16 v[120:123], v[140:143], v[190:193], v[120:123]
	v_mfma_f32_16x16x32_bf16 v[116:119], v[154:157], v[190:193], v[116:119]
	v_mfma_f32_16x16x32_bf16 v[112:115], v[140:143], v[198:201], v[112:115]
	v_mfma_f32_16x16x32_bf16 v[108:111], v[154:157], v[198:201], v[108:111]
	v_mfma_f32_16x16x32_bf16 v[104:107], v[140:143], v[208:211], v[104:107]
	v_mfma_f32_16x16x32_bf16 v[100:103], v[154:157], v[208:211], v[100:103]
	s_setprio 0
	s_setprio 1
	v_mfma_f32_16x16x32_bf16 v[96:99], v[158:161], v[174:177], v[96:99]
	v_mfma_f32_16x16x32_bf16 v[92:95], v[166:169], v[174:177], v[92:95]
	v_mfma_f32_16x16x32_bf16 v[88:91], v[158:161], v[186:189], v[88:91]
	v_mfma_f32_16x16x32_bf16 v[84:87], v[166:169], v[186:189], v[84:87]
	v_mfma_f32_16x16x32_bf16 v[80:83], v[158:161], v[194:197], v[80:83]
	v_mfma_f32_16x16x32_bf16 v[76:79], v[166:169], v[194:197], v[76:79]
	v_mfma_f32_16x16x32_bf16 v[72:75], v[158:161], v[204:207], v[72:75]
	v_mfma_f32_16x16x32_bf16 v[68:71], v[166:169], v[204:207], v[68:71]
	v_mfma_f32_16x16x32_bf16 v[96:99], v[162:165], v[178:181], v[96:99]
	v_mfma_f32_16x16x32_bf16 v[92:95], v[170:173], v[178:181], v[92:95]
	v_mfma_f32_16x16x32_bf16 v[88:91], v[162:165], v[190:193], v[88:91]
	v_mfma_f32_16x16x32_bf16 v[84:87], v[170:173], v[190:193], v[84:87]
	v_mfma_f32_16x16x32_bf16 v[80:83], v[162:165], v[198:201], v[80:83]
	v_mfma_f32_16x16x32_bf16 v[76:79], v[170:173], v[198:201], v[76:79]
	v_mfma_f32_16x16x32_bf16 v[72:75], v[162:165], v[208:211], v[72:75]
	v_mfma_f32_16x16x32_bf16 v[68:71], v[170:173], v[208:211], v[68:71]
	s_setprio 0
	s_barrier
	s_add_i32 s45, s45, s62
	v_lshl_add_u64 v[182:183], s[56:57], 0, v[34:35]
	s_mov_b32 m0, s45
	ds_read_b128 v[174:177], v203 offset:16384
	ds_read_b128 v[178:181], v203 offset:17408
	ds_read_b128 v[186:189], v203 offset:18432
	ds_read_b128 v[190:193], v203 offset:19456
	ds_read_b128 v[194:197], v203 offset:20480
	ds_read_b128 v[198:201], v203 offset:21504
	ds_read_b128 v[204:207], v203 offset:22528
	ds_read_b128 v[208:211], v203 offset:23552
	global_load_lds_dwordx4 v[182:183], off
	s_add_i32 m0, s45, 0x2000
	s_add_u32 vcc_lo, s56, 0x80000
	v_lshl_add_u64 v[212:213], s[56:57], 0, v[148:149]
	s_addc_u32 vcc_hi, s57, 0
	s_add_i32 s45, s47, s62
	global_load_lds_dwordx4 v[212:213], off
	v_lshl_add_u64 v[214:215], vcc, 0, v[34:35]
	s_mov_b32 m0, s45
	v_lshl_add_u64 v[216:217], s[58:59], 0, v[148:149]
	global_load_lds_dwordx4 v[214:215], off
	v_lshl_add_u64 v[214:215], vcc, 0, v[148:149]
	s_add_i32 m0, s45, 0x2000
	s_nop 0
	global_load_lds_dwordx4 v[214:215], off
	v_lshl_add_u64 v[214:215], s[58:59], 0, v[34:35]
	s_mov_b32 m0, s1
	s_nop 0
	global_load_lds_dwordx4 v[214:215], off
	s_mov_b32 m0, s7
	s_nop 0
	global_load_lds_dwordx4 v[216:217], off
	s_waitcnt vmcnt(8)
	s_waitcnt lgkmcnt(0)
	s_barrier
	s_setprio 1
	s_waitcnt lgkmcnt(0)
	v_mfma_f32_16x16x32_bf16 v[64:67], v[136:139], v[174:177], v[64:67]
	v_mfma_f32_16x16x32_bf16 v[60:63], v[144:147], v[174:177], v[60:63]
	v_mfma_f32_16x16x32_bf16 v[56:59], v[136:139], v[186:189], v[56:59]
	v_mfma_f32_16x16x32_bf16 v[52:55], v[144:147], v[186:189], v[52:55]
	v_mfma_f32_16x16x32_bf16 v[48:51], v[136:139], v[194:197], v[48:51]
	v_mfma_f32_16x16x32_bf16 v[44:47], v[144:147], v[194:197], v[44:47]
	v_mfma_f32_16x16x32_bf16 v[40:43], v[136:139], v[204:207], v[40:43]
	v_mfma_f32_16x16x32_bf16 v[36:39], v[144:147], v[204:207], v[36:39]
	v_mfma_f32_16x16x32_bf16 v[64:67], v[140:143], v[178:181], v[64:67]
	v_mfma_f32_16x16x32_bf16 v[60:63], v[154:157], v[178:181], v[60:63]
	v_mfma_f32_16x16x32_bf16 v[56:59], v[140:143], v[190:193], v[56:59]
	v_mfma_f32_16x16x32_bf16 v[52:55], v[154:157], v[190:193], v[52:55]
	v_mfma_f32_16x16x32_bf16 v[48:51], v[140:143], v[198:201], v[48:51]
	v_mfma_f32_16x16x32_bf16 v[44:47], v[154:157], v[198:201], v[44:47]
	v_mfma_f32_16x16x32_bf16 v[40:43], v[140:143], v[208:211], v[40:43]
	v_mfma_f32_16x16x32_bf16 v[36:39], v[154:157], v[208:211], v[36:39]
	s_setprio 0
	s_setprio 1
	v_mfma_f32_16x16x32_bf16 v[30:33], v[158:161], v[174:177], v[30:33]
	v_mfma_f32_16x16x32_bf16 v[26:29], v[166:169], v[174:177], v[26:29]
	v_mfma_f32_16x16x32_bf16 v[22:25], v[158:161], v[186:189], v[22:25]
	v_mfma_f32_16x16x32_bf16 v[18:21], v[166:169], v[186:189], v[18:21]
	v_mfma_f32_16x16x32_bf16 v[14:17], v[158:161], v[194:197], v[14:17]
	v_mfma_f32_16x16x32_bf16 v[10:13], v[166:169], v[194:197], v[10:13]
	v_mfma_f32_16x16x32_bf16 v[6:9], v[158:161], v[204:207], v[6:9]
	v_mfma_f32_16x16x32_bf16 v[2:5], v[166:169], v[204:207], v[2:5]
	v_mfma_f32_16x16x32_bf16 v[30:33], v[162:165], v[178:181], v[30:33]
	v_mfma_f32_16x16x32_bf16 v[26:29], v[170:173], v[178:181], v[26:29]
	v_mfma_f32_16x16x32_bf16 v[22:25], v[162:165], v[190:193], v[22:25]
	v_mfma_f32_16x16x32_bf16 v[18:21], v[170:173], v[190:193], v[18:21]
	v_mfma_f32_16x16x32_bf16 v[14:17], v[162:165], v[198:201], v[14:17]
	v_mfma_f32_16x16x32_bf16 v[10:13], v[170:173], v[198:201], v[10:13]
	v_mfma_f32_16x16x32_bf16 v[6:9], v[162:165], v[208:211], v[6:9]
	v_mfma_f32_16x16x32_bf16 v[2:5], v[170:173], v[208:211], v[2:5]
	s_setprio 0
	s_barrier
	s_add_i32 s45, 0, 0x18000
	s_add_i32 s47, 0, 0x1c000
	v_add_u32_e32 v154, s45, v185
	v_add_u32_e32 v170, s47, v185
	ds_read_b128 v[136:139], v154
	ds_read_b128 v[140:143], v154 offset:1024
	ds_read_b128 v[144:147], v154 offset:2048
	ds_read_b128 v[154:157], v154 offset:3072
	ds_read_b128 v[158:161], v170
	ds_read_b128 v[162:165], v170 offset:1024
	ds_read_b128 v[166:169], v170 offset:2048
	ds_read_b128 v[170:173], v170 offset:3072
	s_add_u32 s58, s58, 0x80000
	s_addc_u32 s59, s59, 0
	s_mov_b32 m0, s65
	v_lshl_add_u64 v[218:219], s[58:59], 0, v[34:35]
	ds_read_b128 v[174:177], v203 offset:32768
	ds_read_b128 v[178:181], v203 offset:33792
	ds_read_b128 v[186:189], v203 offset:34816
	ds_read_b128 v[190:193], v203 offset:35840
	ds_read_b128 v[194:197], v203 offset:36864
	ds_read_b128 v[198:201], v203 offset:37888
	ds_read_b128 v[204:207], v203 offset:38912
	ds_read_b128 v[208:211], v203 offset:39936
	global_load_lds_dwordx4 v[218:219], off
	v_lshl_add_u64 v[218:219], s[58:59], 0, v[148:149]
	s_mov_b32 m0, s66
	s_nop 0
	global_load_lds_dwordx4 v[218:219], off
	s_waitcnt vmcnt(8)
	s_waitcnt lgkmcnt(0)
	s_barrier
	s_setprio 1
	s_waitcnt lgkmcnt(0)
	v_mfma_f32_16x16x32_bf16 v[128:131], v[136:139], v[174:177], v[128:131]
	v_mfma_f32_16x16x32_bf16 v[124:127], v[144:147], v[174:177], v[124:127]
	v_mfma_f32_16x16x32_bf16 v[120:123], v[136:139], v[186:189], v[120:123]
	v_mfma_f32_16x16x32_bf16 v[116:119], v[144:147], v[186:189], v[116:119]
	v_mfma_f32_16x16x32_bf16 v[112:115], v[136:139], v[194:197], v[112:115]
	v_mfma_f32_16x16x32_bf16 v[108:111], v[144:147], v[194:197], v[108:111]
	v_mfma_f32_16x16x32_bf16 v[104:107], v[136:139], v[204:207], v[104:107]
	v_mfma_f32_16x16x32_bf16 v[100:103], v[144:147], v[204:207], v[100:103]
	v_mfma_f32_16x16x32_bf16 v[128:131], v[140:143], v[178:181], v[128:131]
	v_mfma_f32_16x16x32_bf16 v[124:127], v[154:157], v[178:181], v[124:127]
	v_mfma_f32_16x16x32_bf16 v[120:123], v[140:143], v[190:193], v[120:123]
	v_mfma_f32_16x16x32_bf16 v[116:119], v[154:157], v[190:193], v[116:119]
	v_mfma_f32_16x16x32_bf16 v[112:115], v[140:143], v[198:201], v[112:115]
	v_mfma_f32_16x16x32_bf16 v[108:111], v[154:157], v[198:201], v[108:111]
	v_mfma_f32_16x16x32_bf16 v[104:107], v[140:143], v[208:211], v[104:107]
	v_mfma_f32_16x16x32_bf16 v[100:103], v[154:157], v[208:211], v[100:103]
	s_setprio 0
	s_setprio 1
	v_mfma_f32_16x16x32_bf16 v[96:99], v[158:161], v[174:177], v[96:99]
	v_mfma_f32_16x16x32_bf16 v[92:95], v[166:169], v[174:177], v[92:95]
	v_mfma_f32_16x16x32_bf16 v[88:91], v[158:161], v[186:189], v[88:91]
	v_mfma_f32_16x16x32_bf16 v[84:87], v[166:169], v[186:189], v[84:87]
	v_mfma_f32_16x16x32_bf16 v[80:83], v[158:161], v[194:197], v[80:83]
	v_mfma_f32_16x16x32_bf16 v[76:79], v[166:169], v[194:197], v[76:79]
	v_mfma_f32_16x16x32_bf16 v[72:75], v[158:161], v[204:207], v[72:75]
	v_mfma_f32_16x16x32_bf16 v[68:71], v[166:169], v[204:207], v[68:71]
	v_mfma_f32_16x16x32_bf16 v[96:99], v[162:165], v[178:181], v[96:99]
	v_mfma_f32_16x16x32_bf16 v[92:95], v[170:173], v[178:181], v[92:95]
	v_mfma_f32_16x16x32_bf16 v[88:91], v[162:165], v[190:193], v[88:91]
	v_mfma_f32_16x16x32_bf16 v[84:87], v[170:173], v[190:193], v[84:87]
	v_mfma_f32_16x16x32_bf16 v[80:83], v[162:165], v[198:201], v[80:83]
	v_mfma_f32_16x16x32_bf16 v[76:79], v[170:173], v[198:201], v[76:79]
	v_mfma_f32_16x16x32_bf16 v[72:75], v[162:165], v[208:211], v[72:75]
	v_mfma_f32_16x16x32_bf16 v[68:71], v[170:173], v[208:211], v[68:71]
	s_setprio 0
	s_barrier
	s_add_i32 s45, s45, s62
	v_lshl_add_u64 v[182:183], v[182:183], 0, s[96:97]
	s_mov_b32 m0, s45
	ds_read_b128 v[174:177], v203 offset:49152
	ds_read_b128 v[178:181], v203 offset:50176
	ds_read_b128 v[186:189], v203 offset:51200
	ds_read_b128 v[190:193], v203 offset:52224
	ds_read_b128 v[194:197], v203 offset:53248
	ds_read_b128 v[198:201], v203 offset:54272
	ds_read_b128 v[204:207], v203 offset:55296
	ds_read_b128 v[208:211], v203 offset:56320
	global_load_lds_dwordx4 v[182:183], off
	s_add_i32 m0, s45, 0x2000
	s_add_u32 s56, s56, 0x80080
	v_lshl_add_u64 v[182:183], v[212:213], 0, s[96:97]
	s_addc_u32 s57, s57, 0
	s_add_i32 s45, s47, s62
	global_load_lds_dwordx4 v[182:183], off
	v_lshl_add_u64 v[182:183], s[56:57], 0, v[34:35]
	s_mov_b32 m0, s45
	s_nop 0
	global_load_lds_dwordx4 v[182:183], off
	v_lshl_add_u64 v[182:183], s[56:57], 0, v[148:149]
	s_add_i32 m0, s45, 0x2000
	s_nop 0
	global_load_lds_dwordx4 v[182:183], off
	v_lshl_add_u64 v[182:183], v[214:215], 0, s[96:97]
	s_mov_b32 m0, s68
	s_nop 0
	global_load_lds_dwordx4 v[182:183], off
	v_lshl_add_u64 v[182:183], v[216:217], 0, s[96:97]
	s_mov_b32 m0, s69
	s_nop 0
	global_load_lds_dwordx4 v[182:183], off
	s_waitcnt vmcnt(8)
	s_waitcnt lgkmcnt(0)
	s_barrier
	s_setprio 1
	s_waitcnt lgkmcnt(0)
	v_mfma_f32_16x16x32_bf16 v[64:67], v[136:139], v[174:177], v[64:67]
	v_mfma_f32_16x16x32_bf16 v[60:63], v[144:147], v[174:177], v[60:63]
	v_mfma_f32_16x16x32_bf16 v[56:59], v[136:139], v[186:189], v[56:59]
	v_mfma_f32_16x16x32_bf16 v[52:55], v[144:147], v[186:189], v[52:55]
	v_mfma_f32_16x16x32_bf16 v[48:51], v[136:139], v[194:197], v[48:51]
	v_mfma_f32_16x16x32_bf16 v[44:47], v[144:147], v[194:197], v[44:47]
	v_mfma_f32_16x16x32_bf16 v[40:43], v[136:139], v[204:207], v[40:43]
	v_mfma_f32_16x16x32_bf16 v[36:39], v[144:147], v[204:207], v[36:39]
	v_mfma_f32_16x16x32_bf16 v[64:67], v[140:143], v[178:181], v[64:67]
	v_mfma_f32_16x16x32_bf16 v[60:63], v[154:157], v[178:181], v[60:63]
	v_mfma_f32_16x16x32_bf16 v[56:59], v[140:143], v[190:193], v[56:59]
	v_mfma_f32_16x16x32_bf16 v[52:55], v[154:157], v[190:193], v[52:55]
	v_mfma_f32_16x16x32_bf16 v[48:51], v[140:143], v[198:201], v[48:51]
	v_mfma_f32_16x16x32_bf16 v[44:47], v[154:157], v[198:201], v[44:47]
	v_mfma_f32_16x16x32_bf16 v[40:43], v[140:143], v[208:211], v[40:43]
	v_mfma_f32_16x16x32_bf16 v[36:39], v[154:157], v[208:211], v[36:39]
	s_setprio 0
	s_setprio 1
	v_mfma_f32_16x16x32_bf16 v[30:33], v[158:161], v[174:177], v[30:33]
	v_mfma_f32_16x16x32_bf16 v[26:29], v[166:169], v[174:177], v[26:29]
	v_mfma_f32_16x16x32_bf16 v[22:25], v[158:161], v[186:189], v[22:25]
	v_mfma_f32_16x16x32_bf16 v[18:21], v[166:169], v[186:189], v[18:21]
	v_mfma_f32_16x16x32_bf16 v[14:17], v[158:161], v[194:197], v[14:17]
	v_mfma_f32_16x16x32_bf16 v[10:13], v[166:169], v[194:197], v[10:13]
	v_mfma_f32_16x16x32_bf16 v[6:9], v[158:161], v[204:207], v[6:9]
	v_mfma_f32_16x16x32_bf16 v[2:5], v[166:169], v[204:207], v[2:5]
	v_mfma_f32_16x16x32_bf16 v[30:33], v[162:165], v[178:181], v[30:33]
	v_mfma_f32_16x16x32_bf16 v[26:29], v[170:173], v[178:181], v[26:29]
	v_mfma_f32_16x16x32_bf16 v[22:25], v[162:165], v[190:193], v[22:25]
	v_mfma_f32_16x16x32_bf16 v[18:21], v[170:173], v[190:193], v[18:21]
	v_mfma_f32_16x16x32_bf16 v[14:17], v[162:165], v[198:201], v[14:17]
	v_mfma_f32_16x16x32_bf16 v[10:13], v[170:173], v[198:201], v[10:13]
	v_mfma_f32_16x16x32_bf16 v[6:9], v[162:165], v[208:211], v[6:9]
	v_mfma_f32_16x16x32_bf16 v[2:5], v[170:173], v[208:211], v[2:5]
	s_setprio 0
	s_add_i32 s45, s43, 2
	s_add_u32 s54, s54, 0x100
	s_addc_u32 s55, s55, 0
	v_lshl_add_u64 v[134:135], v[134:135], 0, s[28:29]
	v_lshl_add_u64 v[132:133], v[132:133], 0, s[28:29]
	s_cmp_ge_i32 s43, s61
	s_mov_b32 s43, s45
	s_barrier
	s_cbranch_scc0 .LBB0_1248
	s_and_b64 vcc, exec, s[16:17]
	s_cbranch_vccz .LBB0_1251
	s_barrier

.LBB0_1485:
	s_add_u32 s40, s18, 0xfff80080
	s_addc_u32 s41, s19, -1
	s_cmp_eq_u32 s60, 28
	s_cselect_b32 s43, s9, s41
	s_cselect_b32 s42, s56, s40
	s_cselect_b32 s41, s11, s59
	s_cselect_b32 s40, s57, s58
	s_add_i32 s61, 0, 0x10000
	v_add_u32_e32 v142, s61, v145
	s_add_i32 s64, 0, 0x14000
	ds_read_b128 v[148:151], v142
	ds_read_b128 v[152:155], v142 offset:1024
	ds_read_b128 v[156:159], v142 offset:2048
	ds_read_b128 v[160:163], v142 offset:3072
	v_add_u32_e32 v142, s64, v145
	ds_read_b128 v[164:167], v142
	ds_read_b128 v[168:171], v142 offset:1024
	ds_read_b128 v[172:175], v142 offset:2048
	ds_read_b128 v[176:179], v142 offset:3072
	v_lshl_add_u64 v[142:143], s[18:19], 0, v[138:139]
	s_add_i32 m0, s47, 0xc000
	ds_read_b128 v[180:183], v147
	ds_read_b128 v[184:187], v147 offset:1024
	ds_read_b128 v[188:191], v147 offset:2048
	ds_read_b128 v[192:195], v147 offset:3072
	ds_read_b128 v[196:199], v147 offset:4096
	ds_read_b128 v[200:203], v147 offset:5120
	ds_read_b128 v[204:207], v147 offset:6144
	ds_read_b128 v[208:211], v147 offset:7168
	global_load_lds_dwordx4 v[142:143], off
	v_lshl_add_u64 v[142:143], s[18:19], 0, v[140:141]
	s_add_i32 m0, s47, 0xe000
	s_nop 0
	global_load_lds_dwordx4 v[142:143], off
	s_waitcnt vmcnt(8)
	s_waitcnt lgkmcnt(0)
	s_barrier
	s_setprio 1
	s_waitcnt lgkmcnt(0)
	v_mfma_f32_16x16x32_bf16 v[128:131], v[148:151], v[180:183], v[128:131]
	v_mfma_f32_16x16x32_bf16 v[124:127], v[156:159], v[180:183], v[124:127]
	v_mfma_f32_16x16x32_bf16 v[112:115], v[148:151], v[188:191], v[112:115]
	v_mfma_f32_16x16x32_bf16 v[108:111], v[156:159], v[188:191], v[108:111]
	v_mfma_f32_16x16x32_bf16 v[96:99], v[148:151], v[196:199], v[96:99]
	v_mfma_f32_16x16x32_bf16 v[92:95], v[156:159], v[196:199], v[92:95]
	v_mfma_f32_16x16x32_bf16 v[80:83], v[148:151], v[204:207], v[80:83]
	v_mfma_f32_16x16x32_bf16 v[76:79], v[156:159], v[204:207], v[76:79]
	v_mfma_f32_16x16x32_bf16 v[128:131], v[152:155], v[184:187], v[128:131]
	v_mfma_f32_16x16x32_bf16 v[124:127], v[160:163], v[184:187], v[124:127]
	v_mfma_f32_16x16x32_bf16 v[112:115], v[152:155], v[192:195], v[112:115]
	v_mfma_f32_16x16x32_bf16 v[108:111], v[160:163], v[192:195], v[108:111]
	v_mfma_f32_16x16x32_bf16 v[96:99], v[152:155], v[200:203], v[96:99]
	v_mfma_f32_16x16x32_bf16 v[92:95], v[160:163], v[200:203], v[92:95]
	v_mfma_f32_16x16x32_bf16 v[80:83], v[152:155], v[208:211], v[80:83]
	v_mfma_f32_16x16x32_bf16 v[76:79], v[160:163], v[208:211], v[76:79]
	s_setprio 0
	s_setprio 1
	v_mfma_f32_16x16x32_bf16 v[120:123], v[164:167], v[180:183], v[120:123]
	v_mfma_f32_16x16x32_bf16 v[116:119], v[172:175], v[180:183], v[116:119]
	v_mfma_f32_16x16x32_bf16 v[104:107], v[164:167], v[188:191], v[104:107]
	v_mfma_f32_16x16x32_bf16 v[100:103], v[172:175], v[188:191], v[100:103]
	v_mfma_f32_16x16x32_bf16 v[88:91], v[164:167], v[196:199], v[88:91]
	v_mfma_f32_16x16x32_bf16 v[84:87], v[172:175], v[196:199], v[84:87]
	v_mfma_f32_16x16x32_bf16 v[72:75], v[164:167], v[204:207], v[72:75]
	v_mfma_f32_16x16x32_bf16 v[68:71], v[172:175], v[204:207], v[68:71]
	v_mfma_f32_16x16x32_bf16 v[120:123], v[168:171], v[184:187], v[120:123]
	v_mfma_f32_16x16x32_bf16 v[116:119], v[176:179], v[184:187], v[116:119]
	v_mfma_f32_16x16x32_bf16 v[104:107], v[168:171], v[192:195], v[104:107]
	v_mfma_f32_16x16x32_bf16 v[100:103], v[176:179], v[192:195], v[100:103]
	v_mfma_f32_16x16x32_bf16 v[88:91], v[168:171], v[200:203], v[88:91]
	v_mfma_f32_16x16x32_bf16 v[84:87], v[176:179], v[200:203], v[84:87]
	v_mfma_f32_16x16x32_bf16 v[72:75], v[168:171], v[208:211], v[72:75]
	v_mfma_f32_16x16x32_bf16 v[68:71], v[176:179], v[208:211], v[68:71]
	s_setprio 0
	s_barrier
	s_add_i32 s61, s61, s46
	v_lshl_add_u64 v[142:143], s[40:41], 0, v[34:35]
	s_mov_b32 m0, s61
	ds_read_b128 v[180:183], v147 offset:16384
	ds_read_b128 v[184:187], v147 offset:17408
	ds_read_b128 v[188:191], v147 offset:18432
	ds_read_b128 v[192:195], v147 offset:19456
	ds_read_b128 v[196:199], v147 offset:20480
	ds_read_b128 v[200:203], v147 offset:21504
	ds_read_b128 v[204:207], v147 offset:22528
	ds_read_b128 v[208:211], v147 offset:23552
	global_load_lds_dwordx4 v[142:143], off
	s_add_i32 m0, s61, 0x2000
	s_add_u32 s62, s40, 0x80000
	v_lshl_add_u64 v[212:213], s[40:41], 0, v[132:133]
	s_addc_u32 s63, s41, 0
	s_add_i32 s61, s64, s46
	global_load_lds_dwordx4 v[212:213], off
	v_lshl_add_u64 v[214:215], s[62:63], 0, v[34:35]
	s_mov_b32 m0, s61
	v_lshl_add_u64 v[216:217], s[42:43], 0, v[134:135]
	global_load_lds_dwordx4 v[214:215], off
	v_lshl_add_u64 v[214:215], s[62:63], 0, v[132:133]
	s_add_i32 m0, s61, 0x2000
	s_nop 0
	global_load_lds_dwordx4 v[214:215], off
	v_lshl_add_u64 v[214:215], s[42:43], 0, v[136:137]
	s_mov_b32 m0, s47
	s_nop 0
	global_load_lds_dwordx4 v[214:215], off
	s_mov_b32 m0, s48
	s_nop 0
	global_load_lds_dwordx4 v[216:217], off
	s_waitcnt vmcnt(8)
	s_waitcnt lgkmcnt(0)
	s_barrier
	s_setprio 1
	s_waitcnt lgkmcnt(0)
	v_mfma_f32_16x16x32_bf16 v[64:67], v[148:151], v[180:183], v[64:67]
	v_mfma_f32_16x16x32_bf16 v[60:63], v[156:159], v[180:183], v[60:63]
	v_mfma_f32_16x16x32_bf16 v[48:51], v[148:151], v[188:191], v[48:51]
	v_mfma_f32_16x16x32_bf16 v[44:47], v[156:159], v[188:191], v[44:47]
	v_mfma_f32_16x16x32_bf16 v[30:33], v[148:151], v[196:199], v[30:33]
	v_mfma_f32_16x16x32_bf16 v[26:29], v[156:159], v[196:199], v[26:29]
	v_mfma_f32_16x16x32_bf16 v[14:17], v[148:151], v[204:207], v[14:17]
	v_mfma_f32_16x16x32_bf16 v[10:13], v[156:159], v[204:207], v[10:13]
	v_mfma_f32_16x16x32_bf16 v[64:67], v[152:155], v[184:187], v[64:67]
	v_mfma_f32_16x16x32_bf16 v[60:63], v[160:163], v[184:187], v[60:63]
	v_mfma_f32_16x16x32_bf16 v[48:51], v[152:155], v[192:195], v[48:51]
	v_mfma_f32_16x16x32_bf16 v[44:47], v[160:163], v[192:195], v[44:47]
	v_mfma_f32_16x16x32_bf16 v[30:33], v[152:155], v[200:203], v[30:33]
	v_mfma_f32_16x16x32_bf16 v[26:29], v[160:163], v[200:203], v[26:29]
	v_mfma_f32_16x16x32_bf16 v[14:17], v[152:155], v[208:211], v[14:17]
	v_mfma_f32_16x16x32_bf16 v[10:13], v[160:163], v[208:211], v[10:13]
	s_setprio 0
	s_setprio 1
	v_mfma_f32_16x16x32_bf16 v[56:59], v[164:167], v[180:183], v[56:59]
	v_mfma_f32_16x16x32_bf16 v[52:55], v[172:175], v[180:183], v[52:55]
	v_mfma_f32_16x16x32_bf16 v[40:43], v[164:167], v[188:191], v[40:43]
	v_mfma_f32_16x16x32_bf16 v[36:39], v[172:175], v[188:191], v[36:39]
	v_mfma_f32_16x16x32_bf16 v[22:25], v[164:167], v[196:199], v[22:25]
	v_mfma_f32_16x16x32_bf16 v[18:21], v[172:175], v[196:199], v[18:21]
	v_mfma_f32_16x16x32_bf16 v[6:9], v[164:167], v[204:207], v[6:9]
	v_mfma_f32_16x16x32_bf16 v[2:5], v[172:175], v[204:207], v[2:5]
	v_mfma_f32_16x16x32_bf16 v[56:59], v[168:171], v[184:187], v[56:59]
	v_mfma_f32_16x16x32_bf16 v[52:55], v[176:179], v[184:187], v[52:55]
	v_mfma_f32_16x16x32_bf16 v[40:43], v[168:171], v[192:195], v[40:43]
	v_mfma_f32_16x16x32_bf16 v[36:39], v[176:179], v[192:195], v[36:39]
	v_mfma_f32_16x16x32_bf16 v[22:25], v[168:171], v[200:203], v[22:25]
	v_mfma_f32_16x16x32_bf16 v[18:21], v[176:179], v[200:203], v[18:21]
	v_mfma_f32_16x16x32_bf16 v[6:9], v[168:171], v[208:211], v[6:9]
	v_mfma_f32_16x16x32_bf16 v[2:5], v[176:179], v[208:211], v[2:5]
	s_setprio 0
	s_barrier
	s_add_i32 s61, 0, 0x18000
	s_add_i32 s62, 0, 0x1c000
	v_add_u32_e32 v160, s61, v145
	v_add_u32_e32 v176, s62, v145
	ds_read_b128 v[148:151], v160
	ds_read_b128 v[152:155], v160 offset:1024
	ds_read_b128 v[156:159], v160 offset:2048
	ds_read_b128 v[160:163], v160 offset:3072
	ds_read_b128 v[164:167], v176
	ds_read_b128 v[168:171], v176 offset:1024
	ds_read_b128 v[172:175], v176 offset:2048
	ds_read_b128 v[176:179], v176 offset:3072
	s_add_u32 s42, s42, 0x80000
	s_addc_u32 s43, s43, 0
	s_mov_b32 m0, s49
	v_lshl_add_u64 v[218:219], s[42:43], 0, v[136:137]
	ds_read_b128 v[180:183], v147 offset:32768
	ds_read_b128 v[184:187], v147 offset:33792
	ds_read_b128 v[188:191], v147 offset:34816
	ds_read_b128 v[192:195], v147 offset:35840
	ds_read_b128 v[196:199], v147 offset:36864
	ds_read_b128 v[200:203], v147 offset:37888
	ds_read_b128 v[204:207], v147 offset:38912
	ds_read_b128 v[208:211], v147 offset:39936
	global_load_lds_dwordx4 v[218:219], off
	v_lshl_add_u64 v[218:219], s[42:43], 0, v[134:135]
	s_mov_b32 m0, s50
	s_nop 0
	global_load_lds_dwordx4 v[218:219], off
	s_waitcnt vmcnt(8)
	s_waitcnt lgkmcnt(0)
	s_barrier
	s_setprio 1
	s_waitcnt lgkmcnt(0)
	v_mfma_f32_16x16x32_bf16 v[128:131], v[148:151], v[180:183], v[128:131]
	v_mfma_f32_16x16x32_bf16 v[124:127], v[156:159], v[180:183], v[124:127]
	v_mfma_f32_16x16x32_bf16 v[112:115], v[148:151], v[188:191], v[112:115]
	v_mfma_f32_16x16x32_bf16 v[108:111], v[156:159], v[188:191], v[108:111]
	v_mfma_f32_16x16x32_bf16 v[96:99], v[148:151], v[196:199], v[96:99]
	v_mfma_f32_16x16x32_bf16 v[92:95], v[156:159], v[196:199], v[92:95]
	v_mfma_f32_16x16x32_bf16 v[80:83], v[148:151], v[204:207], v[80:83]
	v_mfma_f32_16x16x32_bf16 v[76:79], v[156:159], v[204:207], v[76:79]
	v_mfma_f32_16x16x32_bf16 v[128:131], v[152:155], v[184:187], v[128:131]
	v_mfma_f32_16x16x32_bf16 v[124:127], v[160:163], v[184:187], v[124:127]
	v_mfma_f32_16x16x32_bf16 v[112:115], v[152:155], v[192:195], v[112:115]
	v_mfma_f32_16x16x32_bf16 v[108:111], v[160:163], v[192:195], v[108:111]
	v_mfma_f32_16x16x32_bf16 v[96:99], v[152:155], v[200:203], v[96:99]
	v_mfma_f32_16x16x32_bf16 v[92:95], v[160:163], v[200:203], v[92:95]
	v_mfma_f32_16x16x32_bf16 v[80:83], v[152:155], v[208:211], v[80:83]
	v_mfma_f32_16x16x32_bf16 v[76:79], v[160:163], v[208:211], v[76:79]
	s_setprio 0
	s_setprio 1
	v_mfma_f32_16x16x32_bf16 v[120:123], v[164:167], v[180:183], v[120:123]
	v_mfma_f32_16x16x32_bf16 v[116:119], v[172:175], v[180:183], v[116:119]
	v_mfma_f32_16x16x32_bf16 v[104:107], v[164:167], v[188:191], v[104:107]
	v_mfma_f32_16x16x32_bf16 v[100:103], v[172:175], v[188:191], v[100:103]
	v_mfma_f32_16x16x32_bf16 v[88:91], v[164:167], v[196:199], v[88:91]
	v_mfma_f32_16x16x32_bf16 v[84:87], v[172:175], v[196:199], v[84:87]
	v_mfma_f32_16x16x32_bf16 v[72:75], v[164:167], v[204:207], v[72:75]
	v_mfma_f32_16x16x32_bf16 v[68:71], v[172:175], v[204:207], v[68:71]
	v_mfma_f32_16x16x32_bf16 v[120:123], v[168:171], v[184:187], v[120:123]
	v_mfma_f32_16x16x32_bf16 v[116:119], v[176:179], v[184:187], v[116:119]
	v_mfma_f32_16x16x32_bf16 v[104:107], v[168:171], v[192:195], v[104:107]
	v_mfma_f32_16x16x32_bf16 v[100:103], v[176:179], v[192:195], v[100:103]
	v_mfma_f32_16x16x32_bf16 v[88:91], v[168:171], v[200:203], v[88:91]
	v_mfma_f32_16x16x32_bf16 v[84:87], v[176:179], v[200:203], v[84:87]
	v_mfma_f32_16x16x32_bf16 v[72:75], v[168:171], v[208:211], v[72:75]
	v_mfma_f32_16x16x32_bf16 v[68:71], v[176:179], v[208:211], v[68:71]
	s_setprio 0
	s_barrier
	s_add_i32 s42, s61, s46
	v_lshl_add_u64 v[142:143], v[142:143], 0, s[96:97]
	s_mov_b32 m0, s42
	ds_read_b128 v[180:183], v147 offset:49152
	ds_read_b128 v[184:187], v147 offset:50176
	ds_read_b128 v[188:191], v147 offset:51200
	ds_read_b128 v[192:195], v147 offset:52224
	ds_read_b128 v[196:199], v147 offset:53248
	ds_read_b128 v[200:203], v147 offset:54272
	ds_read_b128 v[204:207], v147 offset:55296
	ds_read_b128 v[208:211], v147 offset:56320
	global_load_lds_dwordx4 v[142:143], off
	s_add_i32 m0, s42, 0x2000
	s_add_u32 s40, s40, 0x80080
	v_lshl_add_u64 v[142:143], v[212:213], 0, s[96:97]
	s_addc_u32 s41, s41, 0
	s_add_i32 s42, s62, s46
	global_load_lds_dwordx4 v[142:143], off
	v_lshl_add_u64 v[142:143], s[40:41], 0, v[34:35]
	s_mov_b32 m0, s42
	s_nop 0
	global_load_lds_dwordx4 v[142:143], off
	v_lshl_add_u64 v[142:143], s[40:41], 0, v[132:133]
	s_add_i32 m0, s42, 0x2000
	s_nop 0
	global_load_lds_dwordx4 v[142:143], off
	v_lshl_add_u64 v[142:143], v[214:215], 0, s[96:97]
	s_mov_b32 m0, s51
	s_nop 0
	global_load_lds_dwordx4 v[142:143], off
	v_lshl_add_u64 v[142:143], v[216:217], 0, s[96:97]
	s_mov_b32 m0, s52
	s_nop 0
	global_load_lds_dwordx4 v[142:143], off
	s_waitcnt vmcnt(8)
	s_waitcnt lgkmcnt(0)
	s_barrier
	s_setprio 1
	s_waitcnt lgkmcnt(0)
	v_mfma_f32_16x16x32_bf16 v[64:67], v[148:151], v[180:183], v[64:67]
	v_mfma_f32_16x16x32_bf16 v[60:63], v[156:159], v[180:183], v[60:63]
	v_mfma_f32_16x16x32_bf16 v[48:51], v[148:151], v[188:191], v[48:51]
	v_mfma_f32_16x16x32_bf16 v[44:47], v[156:159], v[188:191], v[44:47]
	v_mfma_f32_16x16x32_bf16 v[30:33], v[148:151], v[196:199], v[30:33]
	v_mfma_f32_16x16x32_bf16 v[26:29], v[156:159], v[196:199], v[26:29]
	v_mfma_f32_16x16x32_bf16 v[14:17], v[148:151], v[204:207], v[14:17]
	v_mfma_f32_16x16x32_bf16 v[10:13], v[156:159], v[204:207], v[10:13]
	v_mfma_f32_16x16x32_bf16 v[64:67], v[152:155], v[184:187], v[64:67]
	v_mfma_f32_16x16x32_bf16 v[60:63], v[160:163], v[184:187], v[60:63]
	v_mfma_f32_16x16x32_bf16 v[48:51], v[152:155], v[192:195], v[48:51]
	v_mfma_f32_16x16x32_bf16 v[44:47], v[160:163], v[192:195], v[44:47]
	v_mfma_f32_16x16x32_bf16 v[30:33], v[152:155], v[200:203], v[30:33]
	v_mfma_f32_16x16x32_bf16 v[26:29], v[160:163], v[200:203], v[26:29]
	v_mfma_f32_16x16x32_bf16 v[14:17], v[152:155], v[208:211], v[14:17]
	v_mfma_f32_16x16x32_bf16 v[10:13], v[160:163], v[208:211], v[10:13]
	s_setprio 0
	s_setprio 1
	v_mfma_f32_16x16x32_bf16 v[56:59], v[164:167], v[180:183], v[56:59]
	v_mfma_f32_16x16x32_bf16 v[52:55], v[172:175], v[180:183], v[52:55]
	v_mfma_f32_16x16x32_bf16 v[40:43], v[164:167], v[188:191], v[40:43]
	v_mfma_f32_16x16x32_bf16 v[36:39], v[172:175], v[188:191], v[36:39]
	v_mfma_f32_16x16x32_bf16 v[22:25], v[164:167], v[196:199], v[22:25]
	v_mfma_f32_16x16x32_bf16 v[18:21], v[172:175], v[196:199], v[18:21]
	v_mfma_f32_16x16x32_bf16 v[6:9], v[164:167], v[204:207], v[6:9]
	v_mfma_f32_16x16x32_bf16 v[2:5], v[172:175], v[204:207], v[2:5]
	v_mfma_f32_16x16x32_bf16 v[56:59], v[168:171], v[184:187], v[56:59]
	v_mfma_f32_16x16x32_bf16 v[52:55], v[176:179], v[184:187], v[52:55]
	v_mfma_f32_16x16x32_bf16 v[40:43], v[168:171], v[192:195], v[40:43]
	v_mfma_f32_16x16x32_bf16 v[36:39], v[176:179], v[192:195], v[36:39]
	v_mfma_f32_16x16x32_bf16 v[22:25], v[168:171], v[200:203], v[22:25]
	v_mfma_f32_16x16x32_bf16 v[18:21], v[176:179], v[200:203], v[18:21]
	v_mfma_f32_16x16x32_bf16 v[6:9], v[168:171], v[208:211], v[6:9]
	v_mfma_f32_16x16x32_bf16 v[2:5], v[176:179], v[208:211], v[2:5]
	s_setprio 0
	s_add_i32 s60, s60, 2
	s_add_u32 s18, s18, 0x100
	s_addc_u32 s19, s19, 0
	s_add_u32 s58, s58, 0x100
	s_addc_u32 s59, s59, 0
	s_cmp_gt_u32 s60, 29
	s_barrier
	s_cbranch_scc0 .LBB0_1485
	s_and_b64 vcc, exec, s[6:7]
	s_cbranch_vccz .LBB0_1488
	s_barrier

.LBB0_1577:
	s_add_u32 s41, s8, s50
	s_addc_u32 s43, s9, s51
	s_add_u32 s52, s10, s50
	s_addc_u32 s53, s11, s51
	s_cmp_eq_u32 s58, s19
	s_cselect_b32 s55, s47, s43
	s_cselect_b32 s54, s46, s41
	s_cselect_b32 s53, s49, s53
	s_cselect_b32 s52, s48, s52
	s_add_i32 s41, 0, 0x10000
	s_add_i32 s43, 0, 0x14000
	v_add_u32_e32 v154, s41, v185
	v_add_u32_e32 v170, s43, v185
	ds_read_b128 v[136:139], v154
	ds_read_b128 v[140:143], v154 offset:1024
	ds_read_b128 v[144:147], v154 offset:2048
	ds_read_b128 v[154:157], v154 offset:3072
	ds_read_b128 v[158:161], v170
	ds_read_b128 v[162:165], v170 offset:1024
	ds_read_b128 v[166:169], v170 offset:2048
	ds_read_b128 v[170:173], v170 offset:3072
	v_lshl_add_u64 v[182:183], s[8:9], 0, v[134:135]
	s_add_i32 m0, s1, 0xc000
	ds_read_b128 v[174:177], v199
	ds_read_b128 v[178:181], v199 offset:1024
	ds_read_b128 v[186:189], v199 offset:2048
	ds_read_b128 v[190:193], v199 offset:3072
	ds_read_b128 v[194:197], v199 offset:4096
	ds_read_b128 v[200:203], v199 offset:5120
	ds_read_b128 v[204:207], v199 offset:6144
	ds_read_b128 v[208:211], v199 offset:7168
	global_load_lds_dwordx4 v[182:183], off
	v_lshl_add_u64 v[182:183], s[8:9], 0, v[132:133]
	s_add_i32 m0, s1, 0xe000
	s_nop 0
	global_load_lds_dwordx4 v[182:183], off
	s_waitcnt vmcnt(8)
	s_waitcnt lgkmcnt(0)
	s_barrier
	s_setprio 1
	s_waitcnt lgkmcnt(0)
	v_mfma_f32_16x16x32_bf16 v[128:131], v[136:139], v[174:177], v[128:131]
	v_mfma_f32_16x16x32_bf16 v[124:127], v[144:147], v[174:177], v[124:127]
	v_mfma_f32_16x16x32_bf16 v[120:123], v[136:139], v[186:189], v[120:123]
	v_mfma_f32_16x16x32_bf16 v[116:119], v[144:147], v[186:189], v[116:119]
	v_mfma_f32_16x16x32_bf16 v[112:115], v[136:139], v[194:197], v[112:115]
	v_mfma_f32_16x16x32_bf16 v[108:111], v[144:147], v[194:197], v[108:111]
	v_mfma_f32_16x16x32_bf16 v[104:107], v[136:139], v[204:207], v[104:107]
	v_mfma_f32_16x16x32_bf16 v[100:103], v[144:147], v[204:207], v[100:103]
	v_mfma_f32_16x16x32_bf16 v[128:131], v[140:143], v[178:181], v[128:131]
	v_mfma_f32_16x16x32_bf16 v[124:127], v[154:157], v[178:181], v[124:127]
	v_mfma_f32_16x16x32_bf16 v[120:123], v[140:143], v[190:193], v[120:123]
	v_mfma_f32_16x16x32_bf16 v[116:119], v[154:157], v[190:193], v[116:119]
	v_mfma_f32_16x16x32_bf16 v[112:115], v[140:143], v[200:203], v[112:115]
	v_mfma_f32_16x16x32_bf16 v[108:111], v[154:157], v[200:203], v[108:111]
	v_mfma_f32_16x16x32_bf16 v[104:107], v[140:143], v[208:211], v[104:107]
	v_mfma_f32_16x16x32_bf16 v[100:103], v[154:157], v[208:211], v[100:103]
	s_setprio 0
	s_setprio 1
	v_mfma_f32_16x16x32_bf16 v[96:99], v[158:161], v[174:177], v[96:99]
	v_mfma_f32_16x16x32_bf16 v[92:95], v[166:169], v[174:177], v[92:95]
	v_mfma_f32_16x16x32_bf16 v[88:91], v[158:161], v[186:189], v[88:91]
	v_mfma_f32_16x16x32_bf16 v[84:87], v[166:169], v[186:189], v[84:87]
	v_mfma_f32_16x16x32_bf16 v[80:83], v[158:161], v[194:197], v[80:83]
	v_mfma_f32_16x16x32_bf16 v[76:79], v[166:169], v[194:197], v[76:79]
	v_mfma_f32_16x16x32_bf16 v[72:75], v[158:161], v[204:207], v[72:75]
	v_mfma_f32_16x16x32_bf16 v[68:71], v[166:169], v[204:207], v[68:71]
	v_mfma_f32_16x16x32_bf16 v[96:99], v[162:165], v[178:181], v[96:99]
	v_mfma_f32_16x16x32_bf16 v[92:95], v[170:173], v[178:181], v[92:95]
	v_mfma_f32_16x16x32_bf16 v[88:91], v[162:165], v[190:193], v[88:91]
	v_mfma_f32_16x16x32_bf16 v[84:87], v[170:173], v[190:193], v[84:87]
	v_mfma_f32_16x16x32_bf16 v[80:83], v[162:165], v[200:203], v[80:83]
	v_mfma_f32_16x16x32_bf16 v[76:79], v[170:173], v[200:203], v[76:79]
	v_mfma_f32_16x16x32_bf16 v[72:75], v[162:165], v[208:211], v[72:75]
	v_mfma_f32_16x16x32_bf16 v[68:71], v[170:173], v[208:211], v[68:71]
	s_setprio 0
	s_barrier
	s_add_i32 s41, s41, s59
	v_lshl_add_u64 v[182:183], s[52:53], 0, v[34:35]
	s_mov_b32 m0, s41
	ds_read_b128 v[174:177], v199 offset:16384
	ds_read_b128 v[178:181], v199 offset:17408
	ds_read_b128 v[186:189], v199 offset:18432
	ds_read_b128 v[190:193], v199 offset:19456
	ds_read_b128 v[194:197], v199 offset:20480
	ds_read_b128 v[200:203], v199 offset:21504
	ds_read_b128 v[204:207], v199 offset:22528
	ds_read_b128 v[208:211], v199 offset:23552
	global_load_lds_dwordx4 v[182:183], off
	s_add_i32 m0, s41, 0x2000
	s_add_u32 s70, s52, 0x200000
	v_lshl_add_u64 v[212:213], s[52:53], 0, v[148:149]
	s_addc_u32 s71, s53, 0
	s_add_i32 s41, s43, s59
	global_load_lds_dwordx4 v[212:213], off
	v_lshl_add_u64 v[214:215], s[70:71], 0, v[34:35]
	s_mov_b32 m0, s41
	v_lshl_add_u64 v[216:217], s[54:55], 0, v[148:149]
	global_load_lds_dwordx4 v[214:215], off
	v_lshl_add_u64 v[214:215], s[70:71], 0, v[148:149]
	s_add_i32 m0, s41, 0x2000
	s_nop 0
	global_load_lds_dwordx4 v[214:215], off
	v_lshl_add_u64 v[214:215], s[54:55], 0, v[34:35]
	s_mov_b32 m0, s1
	s_nop 0
	global_load_lds_dwordx4 v[214:215], off
	s_mov_b32 m0, s7
	s_nop 0
	global_load_lds_dwordx4 v[216:217], off
	s_waitcnt vmcnt(8)
	s_waitcnt lgkmcnt(0)
	s_barrier
	s_setprio 1
	s_waitcnt lgkmcnt(0)
	v_mfma_f32_16x16x32_bf16 v[64:67], v[136:139], v[174:177], v[64:67]
	v_mfma_f32_16x16x32_bf16 v[60:63], v[144:147], v[174:177], v[60:63]
	v_mfma_f32_16x16x32_bf16 v[56:59], v[136:139], v[186:189], v[56:59]
	v_mfma_f32_16x16x32_bf16 v[52:55], v[144:147], v[186:189], v[52:55]
	v_mfma_f32_16x16x32_bf16 v[48:51], v[136:139], v[194:197], v[48:51]
	v_mfma_f32_16x16x32_bf16 v[44:47], v[144:147], v[194:197], v[44:47]
	v_mfma_f32_16x16x32_bf16 v[40:43], v[136:139], v[204:207], v[40:43]
	v_mfma_f32_16x16x32_bf16 v[36:39], v[144:147], v[204:207], v[36:39]
	v_mfma_f32_16x16x32_bf16 v[64:67], v[140:143], v[178:181], v[64:67]
	v_mfma_f32_16x16x32_bf16 v[60:63], v[154:157], v[178:181], v[60:63]
	v_mfma_f32_16x16x32_bf16 v[56:59], v[140:143], v[190:193], v[56:59]
	v_mfma_f32_16x16x32_bf16 v[52:55], v[154:157], v[190:193], v[52:55]
	v_mfma_f32_16x16x32_bf16 v[48:51], v[140:143], v[200:203], v[48:51]
	v_mfma_f32_16x16x32_bf16 v[44:47], v[154:157], v[200:203], v[44:47]
	v_mfma_f32_16x16x32_bf16 v[40:43], v[140:143], v[208:211], v[40:43]
	v_mfma_f32_16x16x32_bf16 v[36:39], v[154:157], v[208:211], v[36:39]
	s_setprio 0
	s_setprio 1
	v_mfma_f32_16x16x32_bf16 v[30:33], v[158:161], v[174:177], v[30:33]
	v_mfma_f32_16x16x32_bf16 v[26:29], v[166:169], v[174:177], v[26:29]
	v_mfma_f32_16x16x32_bf16 v[22:25], v[158:161], v[186:189], v[22:25]
	v_mfma_f32_16x16x32_bf16 v[18:21], v[166:169], v[186:189], v[18:21]
	v_mfma_f32_16x16x32_bf16 v[14:17], v[158:161], v[194:197], v[14:17]
	v_mfma_f32_16x16x32_bf16 v[10:13], v[166:169], v[194:197], v[10:13]
	v_mfma_f32_16x16x32_bf16 v[6:9], v[158:161], v[204:207], v[6:9]
	v_mfma_f32_16x16x32_bf16 v[2:5], v[166:169], v[204:207], v[2:5]
	v_mfma_f32_16x16x32_bf16 v[30:33], v[162:165], v[178:181], v[30:33]
	v_mfma_f32_16x16x32_bf16 v[26:29], v[170:173], v[178:181], v[26:29]
	v_mfma_f32_16x16x32_bf16 v[22:25], v[162:165], v[190:193], v[22:25]
	v_mfma_f32_16x16x32_bf16 v[18:21], v[170:173], v[190:193], v[18:21]
	v_mfma_f32_16x16x32_bf16 v[14:17], v[162:165], v[200:203], v[14:17]
	v_mfma_f32_16x16x32_bf16 v[10:13], v[170:173], v[200:203], v[10:13]
	v_mfma_f32_16x16x32_bf16 v[6:9], v[162:165], v[208:211], v[6:9]
	v_mfma_f32_16x16x32_bf16 v[2:5], v[170:173], v[208:211], v[2:5]
	s_setprio 0
	s_barrier
	s_add_i32 s41, 0, 0x18000
	s_add_i32 s43, 0, 0x1c000
	v_add_u32_e32 v154, s41, v185
	v_add_u32_e32 v170, s43, v185
	ds_read_b128 v[136:139], v154
	ds_read_b128 v[140:143], v154 offset:1024
	ds_read_b128 v[144:147], v154 offset:2048
	ds_read_b128 v[154:157], v154 offset:3072
	ds_read_b128 v[158:161], v170
	ds_read_b128 v[162:165], v170 offset:1024
	ds_read_b128 v[166:169], v170 offset:2048
	ds_read_b128 v[170:173], v170 offset:3072
	s_add_u32 s54, s54, 0x200000
	s_addc_u32 s55, s55, 0
	s_mov_b32 m0, s62
	v_lshl_add_u64 v[218:219], s[54:55], 0, v[34:35]
	ds_read_b128 v[174:177], v199 offset:32768
	ds_read_b128 v[178:181], v199 offset:33792
	ds_read_b128 v[186:189], v199 offset:34816
	ds_read_b128 v[190:193], v199 offset:35840
	ds_read_b128 v[194:197], v199 offset:36864
	ds_read_b128 v[200:203], v199 offset:37888
	ds_read_b128 v[204:207], v199 offset:38912
	ds_read_b128 v[208:211], v199 offset:39936
	global_load_lds_dwordx4 v[218:219], off
	v_lshl_add_u64 v[218:219], s[54:55], 0, v[148:149]
	s_mov_b32 m0, s63
	s_nop 0
	global_load_lds_dwordx4 v[218:219], off
	s_waitcnt vmcnt(8)
	s_waitcnt lgkmcnt(0)
	s_barrier
	s_setprio 1
	s_waitcnt lgkmcnt(0)
	v_mfma_f32_16x16x32_bf16 v[128:131], v[136:139], v[174:177], v[128:131]
	v_mfma_f32_16x16x32_bf16 v[124:127], v[144:147], v[174:177], v[124:127]
	v_mfma_f32_16x16x32_bf16 v[120:123], v[136:139], v[186:189], v[120:123]
	v_mfma_f32_16x16x32_bf16 v[116:119], v[144:147], v[186:189], v[116:119]
	v_mfma_f32_16x16x32_bf16 v[112:115], v[136:139], v[194:197], v[112:115]
	v_mfma_f32_16x16x32_bf16 v[108:111], v[144:147], v[194:197], v[108:111]
	v_mfma_f32_16x16x32_bf16 v[104:107], v[136:139], v[204:207], v[104:107]
	v_mfma_f32_16x16x32_bf16 v[100:103], v[144:147], v[204:207], v[100:103]
	v_mfma_f32_16x16x32_bf16 v[128:131], v[140:143], v[178:181], v[128:131]
	v_mfma_f32_16x16x32_bf16 v[124:127], v[154:157], v[178:181], v[124:127]
	v_mfma_f32_16x16x32_bf16 v[120:123], v[140:143], v[190:193], v[120:123]
	v_mfma_f32_16x16x32_bf16 v[116:119], v[154:157], v[190:193], v[116:119]
	v_mfma_f32_16x16x32_bf16 v[112:115], v[140:143], v[200:203], v[112:115]
	v_mfma_f32_16x16x32_bf16 v[108:111], v[154:157], v[200:203], v[108:111]
	v_mfma_f32_16x16x32_bf16 v[104:107], v[140:143], v[208:211], v[104:107]
	v_mfma_f32_16x16x32_bf16 v[100:103], v[154:157], v[208:211], v[100:103]
	s_setprio 0
	s_setprio 1
	v_mfma_f32_16x16x32_bf16 v[96:99], v[158:161], v[174:177], v[96:99]
	v_mfma_f32_16x16x32_bf16 v[92:95], v[166:169], v[174:177], v[92:95]
	v_mfma_f32_16x16x32_bf16 v[88:91], v[158:161], v[186:189], v[88:91]
	v_mfma_f32_16x16x32_bf16 v[84:87], v[166:169], v[186:189], v[84:87]
	v_mfma_f32_16x16x32_bf16 v[80:83], v[158:161], v[194:197], v[80:83]
	v_mfma_f32_16x16x32_bf16 v[76:79], v[166:169], v[194:197], v[76:79]
	v_mfma_f32_16x16x32_bf16 v[72:75], v[158:161], v[204:207], v[72:75]
	v_mfma_f32_16x16x32_bf16 v[68:71], v[166:169], v[204:207], v[68:71]
	v_mfma_f32_16x16x32_bf16 v[96:99], v[162:165], v[178:181], v[96:99]
	v_mfma_f32_16x16x32_bf16 v[92:95], v[170:173], v[178:181], v[92:95]
	v_mfma_f32_16x16x32_bf16 v[88:91], v[162:165], v[190:193], v[88:91]
	v_mfma_f32_16x16x32_bf16 v[84:87], v[170:173], v[190:193], v[84:87]
	v_mfma_f32_16x16x32_bf16 v[80:83], v[162:165], v[200:203], v[80:83]
	v_mfma_f32_16x16x32_bf16 v[76:79], v[170:173], v[200:203], v[76:79]
	v_mfma_f32_16x16x32_bf16 v[72:75], v[162:165], v[208:211], v[72:75]
	v_mfma_f32_16x16x32_bf16 v[68:71], v[170:173], v[208:211], v[68:71]
	s_setprio 0
	s_barrier
	s_add_i32 s41, s41, s59
	v_lshl_add_u64 v[182:183], v[182:183], 0, s[96:97]
	s_mov_b32 m0, s41
	ds_read_b128 v[174:177], v199 offset:49152
	ds_read_b128 v[178:181], v199 offset:50176
	ds_read_b128 v[186:189], v199 offset:51200
	ds_read_b128 v[190:193], v199 offset:52224
	ds_read_b128 v[194:197], v199 offset:53248
	ds_read_b128 v[200:203], v199 offset:54272
	ds_read_b128 v[204:207], v199 offset:55296
	ds_read_b128 v[208:211], v199 offset:56320
	global_load_lds_dwordx4 v[182:183], off
	s_add_i32 m0, s41, 0x2000
	s_add_u32 s52, s52, 0x200080
	v_lshl_add_u64 v[182:183], v[212:213], 0, s[96:97]
	s_addc_u32 s53, s53, 0
	s_add_i32 s41, s43, s59
	global_load_lds_dwordx4 v[182:183], off
	v_lshl_add_u64 v[182:183], s[52:53], 0, v[34:35]
	s_mov_b32 m0, s41
	s_nop 0
	global_load_lds_dwordx4 v[182:183], off
	v_lshl_add_u64 v[182:183], s[52:53], 0, v[148:149]
	s_add_i32 m0, s41, 0x2000
	s_nop 0
	global_load_lds_dwordx4 v[182:183], off
	v_lshl_add_u64 v[182:183], v[214:215], 0, s[96:97]
	s_mov_b32 m0, s64
	s_nop 0
	global_load_lds_dwordx4 v[182:183], off
	v_lshl_add_u64 v[182:183], v[216:217], 0, s[96:97]
	s_mov_b32 m0, s65
	s_nop 0
	global_load_lds_dwordx4 v[182:183], off
	s_waitcnt vmcnt(8)
	s_waitcnt lgkmcnt(0)
	s_barrier
	s_setprio 1
	s_waitcnt lgkmcnt(0)
	v_mfma_f32_16x16x32_bf16 v[64:67], v[136:139], v[174:177], v[64:67]
	v_mfma_f32_16x16x32_bf16 v[60:63], v[144:147], v[174:177], v[60:63]
	v_mfma_f32_16x16x32_bf16 v[56:59], v[136:139], v[186:189], v[56:59]
	v_mfma_f32_16x16x32_bf16 v[52:55], v[144:147], v[186:189], v[52:55]
	v_mfma_f32_16x16x32_bf16 v[48:51], v[136:139], v[194:197], v[48:51]
	v_mfma_f32_16x16x32_bf16 v[44:47], v[144:147], v[194:197], v[44:47]
	v_mfma_f32_16x16x32_bf16 v[40:43], v[136:139], v[204:207], v[40:43]
	v_mfma_f32_16x16x32_bf16 v[36:39], v[144:147], v[204:207], v[36:39]
	v_mfma_f32_16x16x32_bf16 v[64:67], v[140:143], v[178:181], v[64:67]
	v_mfma_f32_16x16x32_bf16 v[60:63], v[154:157], v[178:181], v[60:63]
	v_mfma_f32_16x16x32_bf16 v[56:59], v[140:143], v[190:193], v[56:59]
	v_mfma_f32_16x16x32_bf16 v[52:55], v[154:157], v[190:193], v[52:55]
	v_mfma_f32_16x16x32_bf16 v[48:51], v[140:143], v[200:203], v[48:51]
	v_mfma_f32_16x16x32_bf16 v[44:47], v[154:157], v[200:203], v[44:47]
	v_mfma_f32_16x16x32_bf16 v[40:43], v[140:143], v[208:211], v[40:43]
	v_mfma_f32_16x16x32_bf16 v[36:39], v[154:157], v[208:211], v[36:39]
	s_setprio 0
	s_setprio 1
	v_mfma_f32_16x16x32_bf16 v[30:33], v[158:161], v[174:177], v[30:33]
	v_mfma_f32_16x16x32_bf16 v[26:29], v[166:169], v[174:177], v[26:29]
	v_mfma_f32_16x16x32_bf16 v[22:25], v[158:161], v[186:189], v[22:25]
	v_mfma_f32_16x16x32_bf16 v[18:21], v[166:169], v[186:189], v[18:21]
	v_mfma_f32_16x16x32_bf16 v[14:17], v[158:161], v[194:197], v[14:17]
	v_mfma_f32_16x16x32_bf16 v[10:13], v[166:169], v[194:197], v[10:13]
	v_mfma_f32_16x16x32_bf16 v[6:9], v[158:161], v[204:207], v[6:9]
	v_mfma_f32_16x16x32_bf16 v[2:5], v[166:169], v[204:207], v[2:5]
	v_mfma_f32_16x16x32_bf16 v[30:33], v[162:165], v[178:181], v[30:33]
	v_mfma_f32_16x16x32_bf16 v[26:29], v[170:173], v[178:181], v[26:29]
	v_mfma_f32_16x16x32_bf16 v[22:25], v[162:165], v[190:193], v[22:25]
	v_mfma_f32_16x16x32_bf16 v[18:21], v[170:173], v[190:193], v[18:21]
	v_mfma_f32_16x16x32_bf16 v[14:17], v[162:165], v[200:203], v[14:17]
	v_mfma_f32_16x16x32_bf16 v[10:13], v[170:173], v[200:203], v[10:13]
	v_mfma_f32_16x16x32_bf16 v[6:9], v[162:165], v[208:211], v[6:9]
	v_mfma_f32_16x16x32_bf16 v[2:5], v[170:173], v[208:211], v[2:5]
	s_setprio 0
	s_add_i32 s41, s19, 2
	s_add_u32 s50, s50, 0x100
	s_addc_u32 s51, s51, 0
	v_lshl_add_u64 v[134:135], v[134:135], 0, s[28:29]
	v_lshl_add_u64 v[132:133], v[132:133], 0, s[28:29]
	s_cmp_ge_i32 s19, s58
	s_mov_b32 s19, s41
	s_barrier
	s_cbranch_scc0 .LBB0_1577
	s_and_b64 vcc, exec, s[16:17]
	s_cbranch_vccz .LBB0_1580
	s_barrier
